# split-unit merge made role-independent (both partial products rounded before the add) so the result no longer depends on which workgroup finishes second
# speedup vs baseline: 1.0023x; 1.0006x over previous
.Lsp_s1:
	s_or_b64 exec, exec, s[34:35]
	s_barrier
	s_add_u32 s98, s42, 0x20000
	s_addc_u32 s99, s43, 0
	global_load_dwordx2 v[4:5], v2, s[98:99]
	s_waitcnt vmcnt(0)
	v_max_f32_e32 v6, v201, v201
	v_max_f32_e32 v7, v4, v4
	v_max_f32_e32 v6, v6, v7
	v_sub_f32_e32 v7, v201, v6
	v_sub_f32_e32 v8, v4, v6
	v_exp_f32_e32 v7, v7
	v_exp_f32_e32 v8, v8
	v_mov_b32_e32 v201, v6
	v_mul_f32_e32 v232, v232, v7
	v_mul_f32_e32 v5, v5, v8
	v_add_f32_e32 v232, v232, v5
	global_load_dwordx4 v[80:83], v2, s[42:43]
	s_add_u32 s42, s42, 0x2000
	s_addc_u32 s43, s43, 0
	global_load_dwordx4 v[84:87], v2, s[42:43]
	s_add_u32 s42, s42, 0x2000
	s_addc_u32 s43, s43, 0
	global_load_dwordx4 v[88:91], v2, s[42:43]
	s_add_u32 s42, s42, 0x2000
	s_addc_u32 s43, s43, 0
	global_load_dwordx4 v[92:95], v2, s[42:43]
	s_add_u32 s42, s42, 0x2000
	s_addc_u32 s43, s43, 0
	s_waitcnt vmcnt(0)
	v_mul_f32_e32 v16, v16, v7
	v_mul_f32_e32 v80, v80, v8
	v_add_f32_e32 v16, v16, v80
	v_mul_f32_e32 v17, v17, v7
	v_mul_f32_e32 v81, v81, v8
	v_add_f32_e32 v17, v17, v81
	v_mul_f32_e32 v18, v18, v7
	v_mul_f32_e32 v82, v82, v8
	v_add_f32_e32 v18, v18, v82
	v_mul_f32_e32 v19, v19, v7
	v_mul_f32_e32 v83, v83, v8
	v_add_f32_e32 v19, v19, v83
	v_mul_f32_e32 v20, v20, v7
	v_mul_f32_e32 v84, v84, v8
	v_add_f32_e32 v20, v20, v84
	v_mul_f32_e32 v21, v21, v7
	v_mul_f32_e32 v85, v85, v8
	v_add_f32_e32 v21, v21, v85
	v_mul_f32_e32 v22, v22, v7
	v_mul_f32_e32 v86, v86, v8
	v_add_f32_e32 v22, v22, v86
	v_mul_f32_e32 v23, v23, v7
	v_mul_f32_e32 v87, v87, v8
	v_add_f32_e32 v23, v23, v87
	v_mul_f32_e32 v24, v24, v7
	v_mul_f32_e32 v88, v88, v8
	v_add_f32_e32 v24, v24, v88
	v_mul_f32_e32 v25, v25, v7
	v_mul_f32_e32 v89, v89, v8
	v_add_f32_e32 v25, v25, v89
	v_mul_f32_e32 v26, v26, v7
	v_mul_f32_e32 v90, v90, v8
	v_add_f32_e32 v26, v26, v90
	v_mul_f32_e32 v27, v27, v7
	v_mul_f32_e32 v91, v91, v8
	v_add_f32_e32 v27, v27, v91
	v_mul_f32_e32 v28, v28, v7
	v_mul_f32_e32 v92, v92, v8
	v_add_f32_e32 v28, v28, v92
	v_mul_f32_e32 v29, v29, v7
	v_mul_f32_e32 v93, v93, v8
	v_add_f32_e32 v29, v29, v93
	v_mul_f32_e32 v30, v30, v7
	v_mul_f32_e32 v94, v94, v8
	v_add_f32_e32 v30, v30, v94
	v_mul_f32_e32 v31, v31, v7
	v_mul_f32_e32 v95, v95, v8
	v_add_f32_e32 v31, v31, v95
	global_load_dwordx4 v[80:83], v2, s[42:43]
	s_add_u32 s42, s42, 0x2000
	s_addc_u32 s43, s43, 0
	global_load_dwordx4 v[84:87], v2, s[42:43]
	s_add_u32 s42, s42, 0x2000
	s_addc_u32 s43, s43, 0
	global_load_dwordx4 v[88:91], v2, s[42:43]
	s_add_u32 s42, s42, 0x2000
	s_addc_u32 s43, s43, 0
	global_load_dwordx4 v[92:95], v2, s[42:43]
	s_add_u32 s42, s42, 0x2000
	s_addc_u32 s43, s43, 0
	s_waitcnt vmcnt(0)
	v_mul_f32_e32 v32, v32, v7
	v_mul_f32_e32 v80, v80, v8
	v_add_f32_e32 v32, v32, v80
	v_mul_f32_e32 v33, v33, v7
	v_mul_f32_e32 v81, v81, v8
	v_add_f32_e32 v33, v33, v81
	v_mul_f32_e32 v34, v34, v7
	v_mul_f32_e32 v82, v82, v8
	v_add_f32_e32 v34, v34, v82
	v_mul_f32_e32 v35, v35, v7
	v_mul_f32_e32 v83, v83, v8
	v_add_f32_e32 v35, v35, v83
	v_mul_f32_e32 v36, v36, v7
	v_mul_f32_e32 v84, v84, v8
	v_add_f32_e32 v36, v36, v84
	v_mul_f32_e32 v37, v37, v7
	v_mul_f32_e32 v85, v85, v8
	v_add_f32_e32 v37, v37, v85
	v_mul_f32_e32 v38, v38, v7
	v_mul_f32_e32 v86, v86, v8
	v_add_f32_e32 v38, v38, v86
	v_mul_f32_e32 v39, v39, v7
	v_mul_f32_e32 v87, v87, v8
	v_add_f32_e32 v39, v39, v87
	v_mul_f32_e32 v40, v40, v7
	v_mul_f32_e32 v88, v88, v8
	v_add_f32_e32 v40, v40, v88
	v_mul_f32_e32 v41, v41, v7
	v_mul_f32_e32 v89, v89, v8
	v_add_f32_e32 v41, v41, v89
	v_mul_f32_e32 v42, v42, v7
	v_mul_f32_e32 v90, v90, v8
	v_add_f32_e32 v42, v42, v90
	v_mul_f32_e32 v43, v43, v7
	v_mul_f32_e32 v91, v91, v8
	v_add_f32_e32 v43, v43, v91
	v_mul_f32_e32 v44, v44, v7
	v_mul_f32_e32 v92, v92, v8
	v_add_f32_e32 v44, v44, v92
	v_mul_f32_e32 v45, v45, v7
	v_mul_f32_e32 v93, v93, v8
	v_add_f32_e32 v45, v45, v93
	v_mul_f32_e32 v46, v46, v7
	v_mul_f32_e32 v94, v94, v8
	v_add_f32_e32 v46, v46, v94
	v_mul_f32_e32 v47, v47, v7
	v_mul_f32_e32 v95, v95, v8
	v_add_f32_e32 v47, v47, v95
	global_load_dwordx4 v[80:83], v2, s[42:43]
	s_add_u32 s42, s42, 0x2000
	s_addc_u32 s43, s43, 0
	global_load_dwordx4 v[84:87], v2, s[42:43]
	s_add_u32 s42, s42, 0x2000
	s_addc_u32 s43, s43, 0
	global_load_dwordx4 v[88:91], v2, s[42:43]
	s_add_u32 s42, s42, 0x2000
	s_addc_u32 s43, s43, 0
	global_load_dwordx4 v[92:95], v2, s[42:43]
	s_add_u32 s42, s42, 0x2000
	s_addc_u32 s43, s43, 0
	s_waitcnt vmcnt(0)
	v_mul_f32_e32 v48, v48, v7
	v_mul_f32_e32 v80, v80, v8
	v_add_f32_e32 v48, v48, v80
	v_mul_f32_e32 v49, v49, v7
	v_mul_f32_e32 v81, v81, v8
	v_add_f32_e32 v49, v49, v81
	v_mul_f32_e32 v50, v50, v7
	v_mul_f32_e32 v82, v82, v8
	v_add_f32_e32 v50, v50, v82
	v_mul_f32_e32 v51, v51, v7
	v_mul_f32_e32 v83, v83, v8
	v_add_f32_e32 v51, v51, v83
	v_mul_f32_e32 v52, v52, v7
	v_mul_f32_e32 v84, v84, v8
	v_add_f32_e32 v52, v52, v84
	v_mul_f32_e32 v53, v53, v7
	v_mul_f32_e32 v85, v85, v8
	v_add_f32_e32 v53, v53, v85
	v_mul_f32_e32 v54, v54, v7
	v_mul_f32_e32 v86, v86, v8
	v_add_f32_e32 v54, v54, v86
	v_mul_f32_e32 v55, v55, v7
	v_mul_f32_e32 v87, v87, v8
	v_add_f32_e32 v55, v55, v87
	v_mul_f32_e32 v56, v56, v7
	v_mul_f32_e32 v88, v88, v8
	v_add_f32_e32 v56, v56, v88
	v_mul_f32_e32 v57, v57, v7
	v_mul_f32_e32 v89, v89, v8
	v_add_f32_e32 v57, v57, v89
	v_mul_f32_e32 v58, v58, v7
	v_mul_f32_e32 v90, v90, v8
	v_add_f32_e32 v58, v58, v90
	v_mul_f32_e32 v59, v59, v7
	v_mul_f32_e32 v91, v91, v8
	v_add_f32_e32 v59, v59, v91
	v_mul_f32_e32 v60, v60, v7
	v_mul_f32_e32 v92, v92, v8
	v_add_f32_e32 v60, v60, v92
	v_mul_f32_e32 v61, v61, v7
	v_mul_f32_e32 v93, v93, v8
	v_add_f32_e32 v61, v61, v93
	v_mul_f32_e32 v62, v62, v7
	v_mul_f32_e32 v94, v94, v8
	v_add_f32_e32 v62, v62, v94
	v_mul_f32_e32 v63, v63, v7
	v_mul_f32_e32 v95, v95, v8
	v_add_f32_e32 v63, v63, v95
	global_load_dwordx4 v[80:83], v2, s[42:43]
	s_add_u32 s42, s42, 0x2000
	s_addc_u32 s43, s43, 0
	global_load_dwordx4 v[84:87], v2, s[42:43]
	s_add_u32 s42, s42, 0x2000
	s_addc_u32 s43, s43, 0
	global_load_dwordx4 v[88:91], v2, s[42:43]
	s_add_u32 s42, s42, 0x2000
	s_addc_u32 s43, s43, 0
	global_load_dwordx4 v[92:95], v2, s[42:43]
	s_add_u32 s42, s42, 0x2000
	s_addc_u32 s43, s43, 0
	s_waitcnt vmcnt(0)
	v_mul_f32_e32 v64, v64, v7
	v_mul_f32_e32 v80, v80, v8
	v_add_f32_e32 v64, v64, v80
	v_mul_f32_e32 v65, v65, v7
	v_mul_f32_e32 v81, v81, v8
	v_add_f32_e32 v65, v65, v81
	v_mul_f32_e32 v66, v66, v7
	v_mul_f32_e32 v82, v82, v8
	v_add_f32_e32 v66, v66, v82
	v_mul_f32_e32 v67, v67, v7
	v_mul_f32_e32 v83, v83, v8
	v_add_f32_e32 v67, v67, v83
	v_mul_f32_e32 v68, v68, v7
	v_mul_f32_e32 v84, v84, v8
	v_add_f32_e32 v68, v68, v84
	v_mul_f32_e32 v69, v69, v7
	v_mul_f32_e32 v85, v85, v8
	v_add_f32_e32 v69, v69, v85
	v_mul_f32_e32 v70, v70, v7
	v_mul_f32_e32 v86, v86, v8
	v_add_f32_e32 v70, v70, v86
	v_mul_f32_e32 v71, v71, v7
	v_mul_f32_e32 v87, v87, v8
	v_add_f32_e32 v71, v71, v87
	v_mul_f32_e32 v72, v72, v7
	v_mul_f32_e32 v88, v88, v8
	v_add_f32_e32 v72, v72, v88
	v_mul_f32_e32 v73, v73, v7
	v_mul_f32_e32 v89, v89, v8
	v_add_f32_e32 v73, v73, v89
	v_mul_f32_e32 v74, v74, v7
	v_mul_f32_e32 v90, v90, v8
	v_add_f32_e32 v74, v74, v90
	v_mul_f32_e32 v75, v75, v7
	v_mul_f32_e32 v91, v91, v8
	v_add_f32_e32 v75, v75, v91
	v_mul_f32_e32 v76, v76, v7
	v_mul_f32_e32 v92, v92, v8
	v_add_f32_e32 v76, v76, v92
	v_mul_f32_e32 v77, v77, v7
	v_mul_f32_e32 v93, v93, v8
	v_add_f32_e32 v77, v77, v93
	v_mul_f32_e32 v78, v78, v7
	v_mul_f32_e32 v94, v94, v8
	v_add_f32_e32 v78, v78, v94
	v_mul_f32_e32 v79, v79, v7
	v_mul_f32_e32 v95, v95, v8
	v_add_f32_e32 v79, v79, v95
